# speedup vs baseline: 1.0056x; 1.0056x over previous
; __device__ void norm_phase(const float* x32, u16* xn, float* sx, const u16* f, float cmul, const float* gpost,
;                            float* out32, int tid) {
;   const int lane = tid & 63, wv = tid >> 6;
;   const int gw = blockIdx.x * 8 + wv, nw = gridDim.x * 8;
;   float gp[16];
; #pragma unroll
;   for (int e = 0; e < 16; ++e) gp[e] = 0.f;
;   if (f) {
; #pragma unroll
;     for (int i = 0; i < 2; ++i) {
;       float4 a = *(const float4*)(gpost + i * 512 + lane * 8), b = *(const float4*)(gpost + i * 512 + lane * 8 + 4);
;       gp[i * 8 + 0] = a.x; gp[i * 8 + 1] = a.y; gp[i * 8 + 2] = a.z; gp[i * 8 + 3] = a.w;
;       gp[i * 8 + 4] = b.x; gp[i * 8 + 5] = b.y; gp[i * 8 + 6] = b.z; gp[i * 8 + 7] = b.w;
;     }
;   }
;   float4 nx32[4];
;   u32x4 nxb[2], nf[2];
;   float nsx = 1.f;
;     ...
;   if (gw < MTOK) NORM_LOAD(gw);
;   for (int row = gw; row < MTOK; row += nw) {
.Lnf_common:
	v_and_b32_e32 v16, 63, v164
	v_lshrrev_b32_e32 v17, 6, v164
	v_lshlrev_b32_e32 v18, 5, v16
	v_and_b32_e32 v28, 15, v16
	v_readfirstlane_b32 s1, v17
	s_add_u32 s2, s92, s100
	s_addc_u32 s3, s93, 0
	global_load_dwordx4 v[0:3], v18, s[2:3]
	global_load_dwordx4 v[4:7], v18, s[2:3] offset:16
	global_load_dwordx4 v[8:11], v18, s[2:3] offset:2048
	global_load_dwordx4 v[12:15], v18, s[2:3] offset:2064
	s_lshr_b32 s0, s22, 3
	s_and_b32 s2, s0, 7
	s_lshl_b32 s2, s2, 12
	s_lshr_b32 s0, s0, 3
	s_lshl_b32 s0, s0, 7
	s_add_i32 s0, s0, s2
	s_lshl_b32 s3, s1, 4
	s_add_i32 s0, s0, s3
	v_add_u32_e32 v19, s0, v28
	v_lshlrev_b32_e32 v19, 2, v19
	global_load_dword v20, v19, s[34:35]
	v_mov_b32_e32 v21, 0
	s_lshl_b32 s1, s1, 14
	v_lshl_add_u32 v22, v16, 4, s1
	v_lshlrev_b32_e32 v23, 4, v16
	v_add_u32_e32 v24, 0x400, v23
	s_lshl_b32 s4, s0, 11
	s_add_u32 s36, s40, s4
	s_addc_u32 s37, s41, 0
	s_add_u32 s38, s64, s4
	s_addc_u32 s39, s65, 0
	s_movk_i32 s5, 0x800
	s_mov_b64 s[42:43], s[36:37]
	s_mov_b32 s6, 0
	s_add_u32 s80, s36, s6
	s_addc_u32 s81, s37, 0
	s_add_u32 s82, s38, s6
	s_addc_u32 s83, s39, 0
	s_mov_b32 s88, s1
	s_mov_b32 m0, s88
	s_nop 0
	global_load_lds_dwordx4 v23, s[80:81]
	s_add_i32 s89, s88, 0x400
	s_mov_b32 m0, s89
	s_nop 0
	global_load_lds_dwordx4 v24, s[80:81]
	s_add_i32 s89, s88, 0x800
	s_mov_b32 m0, s89
	s_nop 0
	global_load_lds_dwordx4 v23, s[82:83]
	s_add_i32 s89, s88, 0xc00
	s_mov_b32 m0, s89
	s_nop 0
	global_load_lds_dwordx4 v24, s[82:83]
	global_load_dword v26, v19, s[34:35]
	global_load_dword v27, v19, s[34:35]
	s_mov_b32 s6, s5
	s_add_u32 s80, s36, s6
	s_addc_u32 s81, s37, 0
	s_add_u32 s82, s38, s6
	s_addc_u32 s83, s39, 0
	s_add_i32 s88, s1, 0x1000
	s_mov_b32 m0, s88
	s_nop 0
	global_load_lds_dwordx4 v23, s[80:81]
	s_add_i32 s89, s88, 0x400
	s_mov_b32 m0, s89
	s_nop 0
	global_load_lds_dwordx4 v24, s[80:81]
	s_add_i32 s89, s88, 0x800
	s_mov_b32 m0, s89
	s_nop 0
	global_load_lds_dwordx4 v23, s[82:83]
	s_add_i32 s89, s88, 0xc00
	s_mov_b32 m0, s89
	s_nop 0
	global_load_lds_dwordx4 v24, s[82:83]
	global_load_dword v26, v19, s[34:35]
	global_load_dword v27, v19, s[34:35]
	s_lshl_b32 s6, s5, 1
	s_add_u32 s80, s36, s6
	s_addc_u32 s81, s37, 0
	s_add_u32 s82, s38, s6
	s_addc_u32 s83, s39, 0
	s_add_i32 s88, s1, 0x2000
	s_mov_b32 m0, s88
	s_nop 0
	global_load_lds_dwordx4 v23, s[80:81]
	s_add_i32 s89, s88, 0x400
	s_mov_b32 m0, s89
	s_nop 0
	global_load_lds_dwordx4 v24, s[80:81]
	s_add_i32 s89, s88, 0x800
	s_mov_b32 m0, s89
	s_nop 0
	global_load_lds_dwordx4 v23, s[82:83]
	s_add_i32 s89, s88, 0xc00
	s_mov_b32 m0, s89
	s_nop 0
	global_load_lds_dwordx4 v24, s[82:83]
	s_mov_b32 s7, 0
